# residual GEMM epilogue: next row group's residual loads issued after the stats wait, per-group vmcnt(0) replaced by counted waits (vmcnt(4) / vmcnt(2)) so one row group of loads stays in flight
# speedup vs baseline: 1.0331x; 1.0018x over previous
; __device__ __forceinline__ float bflo(unsigned w) { return __uint_as_float(w << 16); }
; __device__ __forceinline__ float bfhi(unsigned w) { return __uint_as_float(w & 0xffff0000u); }
; __device__ __forceinline__ float hlo(unsigned w) { return (float)__builtin_bit_cast(h16x2, w)[0]; }
; __device__ __forceinline__ float hhi(unsigned w) { return (float)__builtin_bit_cast(h16x2, w)[1]; }
;     __device__ __forceinline__ void operator()(const Acc& acc, const Unit& u, int wr, int wc, int fr, int fq) const {
;     ...
;             if (gidx + 1 < 8) { const int ai2 = (gidx + 1) >> 2, m2 = (gidx + 1) & 3; const size_t row2 = (size_t)(row0 + ai2 * 128 + m2 * 16);
; #pragma unroll
;                 for (int bj = 0; bj < 2; ++bj) xv[(gidx + 1) & 1][bj] = *(const u32x4*)(xr + row2 * DM + col0 + bj * 128);
;                 mu[(gidx + 1) & 1] = 0.f; rs[(gidx + 1) & 1] = 1.f;
;                 if (stats) { mu[(gidx + 1) & 1] = stats[row2 * 2]; rs[(gidx + 1) & 1] = stats[row2 * 2 + 1]; } }
;             const size_t rb = (size_t)(row0 + ai * 128 + m * 16) * DM + col0;
; #pragma unroll
;             for (int bj = 0; bj < 2; ++bj) { const u32x4 x4 = xv[gidx & 1][bj];
;                 f32x4 r0, r1;
;                 if (x_bf16) { r0 = (f32x4){bflo(x4.x), bfhi(x4.x), bflo(x4.y), bfhi(x4.y)}; r1 = (f32x4){bflo(x4.z), bfhi(x4.z), bflo(x4.w), bfhi(x4.w)}; }
;                 else { r0 = (f32x4){hlo(x4.x), hhi(x4.x), hlo(x4.y), hhi(x4.y)}; r1 = (f32x4){hlo(x4.z), hhi(x4.z), hlo(x4.w), hhi(x4.w)}; }
;                 if (stats) { r0 = (r0 - mu[gidx & 1]) * rs[gidx & 1] * gv[bj][0] + bv[bj][0]; r1 = (r1 - mu[gidx & 1]) * rs[gidx & 1] * gv[bj][1] + bv[bj][1]; }
;                 const f32x4 o0 = r0 * ALPHA + acc[ai][bj][m][0] * scale, o1 = r1 * ALPHA + acc[ai][bj][m][1] * scale;
;                 u32x4 w; w.x = pkh(o0[0], o0[1]); w.y = pkh(o0[2], o0[3]); w.z = pkh(o1[0], o1[1]); w.w = pkh(o1[2], o1[3]);
;                 *(u32x4*)(op + rb + bj * 128) = w; }
.LBB0_608:
	v_pk_mul_f32 v[154:155], v[154:155], s[62:63] op_sel_hi:[1,0]
	v_pk_mul_f32 v[152:153], v[152:153], s[62:63] op_sel_hi:[1,0]
	v_pk_fma_f32 v[150:151], v[150:151], s[28:29], v[154:155]
	v_pk_fma_f32 v[148:149], v[148:149], s[16:17], v[152:153]
	v_pk_mul_f32 v[152:153], v[158:159], s[62:63] op_sel_hi:[1,0]
	v_pk_mul_f32 v[154:155], v[156:157], s[62:63] op_sel_hi:[1,0]
	v_pk_fma_f32 v[152:153], v[146:147], s[28:29], v[152:153]
	v_pk_fma_f32 v[146:147], v[144:145], s[16:17], v[154:155]
	v_cvt_pk_f16_f32 v144, v148, v149
	v_cvt_pk_f16_f32 v146, v146, v147
	v_cvt_pk_f16_f32 v147, v152, v153
	v_or_b32_e32 v152, 32, v220
	v_ashrrev_i32_e32 v153, 31, v152
	v_cvt_pk_f16_f32 v145, v150, v151
	v_lshlrev_b64 v[172:173], 12, v[152:153]
	global_store_dwordx4 v[182:183], v[144:147], off offset:256
	v_mov_b32_e32 v168, v185
	s_and_b64 vcc, exec, s[8:9]
	v_lshl_add_u64 v[144:145], v[218:219], 0, v[172:173]
	v_mov_b64_e32 v[170:171], v[186:187]
	s_cbranch_vccnz .LBB0_610
	v_lshl_add_u64 v[152:153], v[152:153], 3, s[14:15]
	global_load_dwordx2 v[168:169], v[152:153], off
	v_mov_b32_e32 v171, v187
	s_waitcnt vmcnt(0)
	v_mov_b32_e32 v170, v169
.LBB0_610:
	global_load_dwordx4 v[148:151], v[144:145], off
	s_nop 0
	global_load_dwordx4 v[144:147], v[144:145], off offset:256
	s_waitcnt vmcnt(4)
	s_mov_b64 s[0:1], -1
	s_and_b64 vcc, exec, s[12:13]
	s_cbranch_vccnz .LBB0_679
	s_andn2_b64 vcc, exec, s[0:1]
	s_cbranch_vccz .LBB0_680

; __device__ __forceinline__ float bflo(unsigned w) { return __uint_as_float(w << 16); }
; __device__ __forceinline__ float bfhi(unsigned w) { return __uint_as_float(w & 0xffff0000u); }
; __device__ __forceinline__ float hlo(unsigned w) { return (float)__builtin_bit_cast(h16x2, w)[0]; }
; __device__ __forceinline__ float hhi(unsigned w) { return (float)__builtin_bit_cast(h16x2, w)[1]; }
;     __device__ __forceinline__ void operator()(const Acc& acc, const Unit& u, int wr, int wc, int fr, int fq) const {
;     ...
;             if (gidx + 1 < 8) { const int ai2 = (gidx + 1) >> 2, m2 = (gidx + 1) & 3; const size_t row2 = (size_t)(row0 + ai2 * 128 + m2 * 16);
; #pragma unroll
;                 for (int bj = 0; bj < 2; ++bj) xv[(gidx + 1) & 1][bj] = *(const u32x4*)(xr + row2 * DM + col0 + bj * 128);
;                 mu[(gidx + 1) & 1] = 0.f; rs[(gidx + 1) & 1] = 1.f;
;                 if (stats) { mu[(gidx + 1) & 1] = stats[row2 * 2]; rs[(gidx + 1) & 1] = stats[row2 * 2 + 1]; } }
;             const size_t rb = (size_t)(row0 + ai * 128 + m * 16) * DM + col0;
; #pragma unroll
;             for (int bj = 0; bj < 2; ++bj) { const u32x4 x4 = xv[gidx & 1][bj];
;                 f32x4 r0, r1;
;                 if (x_bf16) { r0 = (f32x4){bflo(x4.x), bfhi(x4.x), bflo(x4.y), bfhi(x4.y)}; r1 = (f32x4){bflo(x4.z), bfhi(x4.z), bflo(x4.w), bfhi(x4.w)}; }
;                 else { r0 = (f32x4){hlo(x4.x), hhi(x4.x), hlo(x4.y), hhi(x4.y)}; r1 = (f32x4){hlo(x4.z), hhi(x4.z), hlo(x4.w), hhi(x4.w)}; }
;                 if (stats) { r0 = (r0 - mu[gidx & 1]) * rs[gidx & 1] * gv[bj][0] + bv[bj][0]; r1 = (r1 - mu[gidx & 1]) * rs[gidx & 1] * gv[bj][1] + bv[bj][1]; }
;                 const f32x4 o0 = r0 * ALPHA + acc[ai][bj][m][0] * scale, o1 = r1 * ALPHA + acc[ai][bj][m][1] * scale;
;                 u32x4 w; w.x = pkh(o0[0], o0[1]); w.y = pkh(o0[2], o0[3]); w.z = pkh(o1[0], o1[1]); w.w = pkh(o1[2], o1[3]);
;                 *(u32x4*)(op + rb + bj * 128) = w; }
.LBB0_618:
	v_pk_mul_f32 v[138:139], v[138:139], s[62:63] op_sel_hi:[1,0]
	v_pk_mul_f32 v[136:137], v[136:137], s[62:63] op_sel_hi:[1,0]
	v_pk_fma_f32 v[134:135], v[134:135], s[28:29], v[138:139]
	v_pk_fma_f32 v[132:133], v[132:133], s[16:17], v[136:137]
	v_pk_mul_f32 v[136:137], v[142:143], s[62:63] op_sel_hi:[1,0]
	v_pk_mul_f32 v[138:139], v[140:141], s[62:63] op_sel_hi:[1,0]
	v_pk_fma_f32 v[136:137], v[130:131], s[28:29], v[136:137]
	v_pk_fma_f32 v[130:131], v[128:129], s[16:17], v[138:139]
	v_cvt_pk_f16_f32 v128, v132, v133
	v_cvt_pk_f16_f32 v130, v130, v131
	v_cvt_pk_f16_f32 v131, v136, v137
	v_or_b32_e32 v136, 48, v220
	v_ashrrev_i32_e32 v137, 31, v136
	v_cvt_pk_f16_f32 v129, v134, v135
	v_lshlrev_b64 v[154:155], 12, v[136:137]
	global_store_dwordx4 v[166:167], v[128:131], off offset:256
	v_mov_b32_e32 v153, v185
	s_and_b64 vcc, exec, s[8:9]
	v_lshl_add_u64 v[128:129], v[218:219], 0, v[154:155]
	v_mov_b32_e32 v157, v186
	s_cbranch_vccnz .LBB0_620
	v_lshl_add_u64 v[136:137], v[136:137], 3, s[14:15]
	global_load_dwordx2 v[156:157], v[136:137], off
	s_waitcnt vmcnt(0)
	v_mov_b32_e32 v153, v156
.LBB0_620:
	global_load_dwordx4 v[132:135], v[128:129], off
	s_nop 0
	global_load_dwordx4 v[128:131], v[128:129], off offset:256
	s_waitcnt vmcnt(4)
	s_mov_b64 s[0:1], -1
	s_and_b64 vcc, exec, s[12:13]
	s_cbranch_vccnz .LBB0_683
	s_andn2_b64 vcc, exec, s[0:1]
	s_cbranch_vccz .LBB0_684
.LBB0_622:
	s_waitcnt vmcnt(4)
	v_mov_b32_e32 v148, v170
	s_and_b64 vcc, exec, s[8:9]
	v_mov_b32_e32 v149, v170
	s_cbranch_vccnz .LBB0_624

; __device__ __forceinline__ float bflo(unsigned w) { return __uint_as_float(w << 16); }
; __device__ __forceinline__ float bfhi(unsigned w) { return __uint_as_float(w & 0xffff0000u); }
; __device__ __forceinline__ float hlo(unsigned w) { return (float)__builtin_bit_cast(h16x2, w)[0]; }
; __device__ __forceinline__ float hhi(unsigned w) { return (float)__builtin_bit_cast(h16x2, w)[1]; }
;     __device__ __forceinline__ void operator()(const Acc& acc, const Unit& u, int wr, int wc, int fr, int fq) const {
;     ...
;             if (gidx + 1 < 8) { const int ai2 = (gidx + 1) >> 2, m2 = (gidx + 1) & 3; const size_t row2 = (size_t)(row0 + ai2 * 128 + m2 * 16);
; #pragma unroll
;                 for (int bj = 0; bj < 2; ++bj) xv[(gidx + 1) & 1][bj] = *(const u32x4*)(xr + row2 * DM + col0 + bj * 128);
;                 mu[(gidx + 1) & 1] = 0.f; rs[(gidx + 1) & 1] = 1.f;
;                 if (stats) { mu[(gidx + 1) & 1] = stats[row2 * 2]; rs[(gidx + 1) & 1] = stats[row2 * 2 + 1]; } }
;             const size_t rb = (size_t)(row0 + ai * 128 + m * 16) * DM + col0;
; #pragma unroll
;             for (int bj = 0; bj < 2; ++bj) { const u32x4 x4 = xv[gidx & 1][bj];
;                 f32x4 r0, r1;
;                 if (x_bf16) { r0 = (f32x4){bflo(x4.x), bfhi(x4.x), bflo(x4.y), bfhi(x4.y)}; r1 = (f32x4){bflo(x4.z), bfhi(x4.z), bflo(x4.w), bfhi(x4.w)}; }
;                 else { r0 = (f32x4){hlo(x4.x), hhi(x4.x), hlo(x4.y), hhi(x4.y)}; r1 = (f32x4){hlo(x4.z), hhi(x4.z), hlo(x4.w), hhi(x4.w)}; }
;                 if (stats) { r0 = (r0 - mu[gidx & 1]) * rs[gidx & 1] * gv[bj][0] + bv[bj][0]; r1 = (r1 - mu[gidx & 1]) * rs[gidx & 1] * gv[bj][1] + bv[bj][1]; }
;                 const f32x4 o0 = r0 * ALPHA + acc[ai][bj][m][0] * scale, o1 = r1 * ALPHA + acc[ai][bj][m][1] * scale;
;                 u32x4 w; w.x = pkh(o0[0], o0[1]); w.y = pkh(o0[2], o0[3]); w.z = pkh(o1[0], o1[1]); w.w = pkh(o1[2], o1[3]);
;                 *(u32x4*)(op + rb + bj * 128) = w; }
.LBB0_628:
	v_pk_mul_f32 v[122:123], v[122:123], s[62:63] op_sel_hi:[1,0]
	v_pk_mul_f32 v[120:121], v[120:121], s[62:63] op_sel_hi:[1,0]
	v_pk_fma_f32 v[118:119], v[118:119], s[28:29], v[122:123]
	v_pk_fma_f32 v[116:117], v[116:117], s[16:17], v[120:121]
	v_pk_mul_f32 v[120:121], v[126:127], s[62:63] op_sel_hi:[1,0]
	v_pk_mul_f32 v[122:123], v[124:125], s[62:63] op_sel_hi:[1,0]
	v_add_u32_e32 v136, 0x80, v220
	v_pk_fma_f32 v[120:121], v[114:115], s[28:29], v[120:121]
	v_pk_fma_f32 v[114:115], v[112:113], s[16:17], v[122:123]
	v_ashrrev_i32_e32 v137, 31, v136
	v_cvt_pk_f16_f32 v112, v116, v117
	v_cvt_pk_f16_f32 v113, v118, v119
	v_cvt_pk_f16_f32 v114, v114, v115
	v_cvt_pk_f16_f32 v115, v120, v121
	v_lshlrev_b64 v[142:143], 12, v[136:137]
	global_store_dwordx4 v[150:151], v[112:115], off offset:256
	v_mov_b32_e32 v187, v157
	v_mov_b32_e32 v138, v185
	v_lshl_add_u64 v[112:113], v[218:219], 0, v[142:143]
	s_and_b64 vcc, exec, s[8:9]
	v_mov_b64_e32 v[140:141], v[186:187]
	s_cbranch_vccnz .LBB0_630
	v_lshl_add_u64 v[120:121], v[136:137], 3, s[14:15]
	global_load_dwordx2 v[138:139], v[120:121], off
	s_waitcnt vmcnt(0)
	v_mov_b32_e32 v156, v139
	v_mov_b64_e32 v[140:141], v[156:157]
.LBB0_630:
	global_load_dwordx4 v[116:119], v[112:113], off
	s_nop 0
	global_load_dwordx4 v[112:115], v[112:113], off offset:256
	s_waitcnt vmcnt(4)
	s_mov_b64 s[0:1], -1
	s_and_b64 vcc, exec, s[12:13]
	s_cbranch_vccnz .LBB0_687
	s_andn2_b64 vcc, exec, s[0:1]
	s_cbranch_vccz .LBB0_688

; __device__ __forceinline__ float bflo(unsigned w) { return __uint_as_float(w << 16); }
; __device__ __forceinline__ float bfhi(unsigned w) { return __uint_as_float(w & 0xffff0000u); }
; __device__ __forceinline__ float hlo(unsigned w) { return (float)__builtin_bit_cast(h16x2, w)[0]; }
; __device__ __forceinline__ float hhi(unsigned w) { return (float)__builtin_bit_cast(h16x2, w)[1]; }
;     __device__ __forceinline__ void operator()(const Acc& acc, const Unit& u, int wr, int wc, int fr, int fq) const {
;     ...
;             if (gidx + 1 < 8) { const int ai2 = (gidx + 1) >> 2, m2 = (gidx + 1) & 3; const size_t row2 = (size_t)(row0 + ai2 * 128 + m2 * 16);
; #pragma unroll
;                 for (int bj = 0; bj < 2; ++bj) xv[(gidx + 1) & 1][bj] = *(const u32x4*)(xr + row2 * DM + col0 + bj * 128);
;                 mu[(gidx + 1) & 1] = 0.f; rs[(gidx + 1) & 1] = 1.f;
;                 if (stats) { mu[(gidx + 1) & 1] = stats[row2 * 2]; rs[(gidx + 1) & 1] = stats[row2 * 2 + 1]; } }
;             const size_t rb = (size_t)(row0 + ai * 128 + m * 16) * DM + col0;
; #pragma unroll
;             for (int bj = 0; bj < 2; ++bj) { const u32x4 x4 = xv[gidx & 1][bj];
;                 f32x4 r0, r1;
;                 if (x_bf16) { r0 = (f32x4){bflo(x4.x), bfhi(x4.x), bflo(x4.y), bfhi(x4.y)}; r1 = (f32x4){bflo(x4.z), bfhi(x4.z), bflo(x4.w), bfhi(x4.w)}; }
;                 else { r0 = (f32x4){hlo(x4.x), hhi(x4.x), hlo(x4.y), hhi(x4.y)}; r1 = (f32x4){hlo(x4.z), hhi(x4.z), hlo(x4.w), hhi(x4.w)}; }
;                 if (stats) { r0 = (r0 - mu[gidx & 1]) * rs[gidx & 1] * gv[bj][0] + bv[bj][0]; r1 = (r1 - mu[gidx & 1]) * rs[gidx & 1] * gv[bj][1] + bv[bj][1]; }
;                 const f32x4 o0 = r0 * ALPHA + acc[ai][bj][m][0] * scale, o1 = r1 * ALPHA + acc[ai][bj][m][1] * scale;
;                 u32x4 w; w.x = pkh(o0[0], o0[1]); w.y = pkh(o0[2], o0[3]); w.z = pkh(o1[0], o1[1]); w.w = pkh(o1[2], o1[3]);
;                 *(u32x4*)(op + rb + bj * 128) = w; }
.LBB0_638:
	v_pk_mul_f32 v[106:107], v[106:107], s[62:63] op_sel_hi:[1,0]
	v_pk_mul_f32 v[104:105], v[104:105], s[62:63] op_sel_hi:[1,0]
	v_pk_fma_f32 v[102:103], v[102:103], s[28:29], v[106:107]
	v_pk_fma_f32 v[100:101], v[100:101], s[16:17], v[104:105]
	v_pk_mul_f32 v[104:105], v[110:111], s[62:63] op_sel_hi:[1,0]
	v_pk_mul_f32 v[106:107], v[108:109], s[62:63] op_sel_hi:[1,0]
	v_pk_fma_f32 v[104:105], v[98:99], s[28:29], v[104:105]
	v_pk_fma_f32 v[98:99], v[96:97], s[16:17], v[106:107]
	v_cvt_pk_f16_f32 v96, v100, v101
	v_cvt_pk_f16_f32 v98, v98, v99
	v_cvt_pk_f16_f32 v99, v104, v105
	v_or_b32_e32 v104, 16, v136
	v_ashrrev_i32_e32 v105, 31, v104
	v_cvt_pk_f16_f32 v97, v102, v103
	v_lshlrev_b64 v[122:123], 12, v[104:105]
	global_store_dwordx4 v[134:135], v[96:99], off offset:256
	v_mov_b32_e32 v121, v185
	s_and_b64 vcc, exec, s[8:9]
	v_lshl_add_u64 v[96:97], v[218:219], 0, v[122:123]
	v_mov_b32_e32 v125, v186
	s_cbranch_vccnz .LBB0_640
	v_lshl_add_u64 v[104:105], v[104:105], 3, s[14:15]
	global_load_dwordx2 v[124:125], v[104:105], off
	s_waitcnt vmcnt(0)
	v_mov_b32_e32 v121, v124
.LBB0_640:
	global_load_dwordx4 v[100:103], v[96:97], off
	s_nop 0
	global_load_dwordx4 v[96:99], v[96:97], off offset:256
	s_waitcnt vmcnt(4)
	s_mov_b64 s[0:1], -1
	s_and_b64 vcc, exec, s[12:13]
	s_cbranch_vccnz .LBB0_691
	s_andn2_b64 vcc, exec, s[0:1]
	s_cbranch_vccz .LBB0_692
.LBB0_642:
	s_waitcnt vmcnt(4)
	v_mov_b32_e32 v116, v140
	s_and_b64 vcc, exec, s[8:9]
	v_mov_b32_e32 v117, v140
	s_cbranch_vccnz .LBB0_644

; __device__ __forceinline__ float bflo(unsigned w) { return __uint_as_float(w << 16); }
; __device__ __forceinline__ float bfhi(unsigned w) { return __uint_as_float(w & 0xffff0000u); }
; __device__ __forceinline__ float hlo(unsigned w) { return (float)__builtin_bit_cast(h16x2, w)[0]; }
; __device__ __forceinline__ float hhi(unsigned w) { return (float)__builtin_bit_cast(h16x2, w)[1]; }
;     __device__ __forceinline__ void operator()(const Acc& acc, const Unit& u, int wr, int wc, int fr, int fq) const {
;     ...
;             if (gidx + 1 < 8) { const int ai2 = (gidx + 1) >> 2, m2 = (gidx + 1) & 3; const size_t row2 = (size_t)(row0 + ai2 * 128 + m2 * 16);
; #pragma unroll
;                 for (int bj = 0; bj < 2; ++bj) xv[(gidx + 1) & 1][bj] = *(const u32x4*)(xr + row2 * DM + col0 + bj * 128);
;                 mu[(gidx + 1) & 1] = 0.f; rs[(gidx + 1) & 1] = 1.f;
;                 if (stats) { mu[(gidx + 1) & 1] = stats[row2 * 2]; rs[(gidx + 1) & 1] = stats[row2 * 2 + 1]; } }
;             const size_t rb = (size_t)(row0 + ai * 128 + m * 16) * DM + col0;
; #pragma unroll
;             for (int bj = 0; bj < 2; ++bj) { const u32x4 x4 = xv[gidx & 1][bj];
;                 f32x4 r0, r1;
;                 if (x_bf16) { r0 = (f32x4){bflo(x4.x), bfhi(x4.x), bflo(x4.y), bfhi(x4.y)}; r1 = (f32x4){bflo(x4.z), bfhi(x4.z), bflo(x4.w), bfhi(x4.w)}; }
;                 else { r0 = (f32x4){hlo(x4.x), hhi(x4.x), hlo(x4.y), hhi(x4.y)}; r1 = (f32x4){hlo(x4.z), hhi(x4.z), hlo(x4.w), hhi(x4.w)}; }
;                 if (stats) { r0 = (r0 - mu[gidx & 1]) * rs[gidx & 1] * gv[bj][0] + bv[bj][0]; r1 = (r1 - mu[gidx & 1]) * rs[gidx & 1] * gv[bj][1] + bv[bj][1]; }
;                 const f32x4 o0 = r0 * ALPHA + acc[ai][bj][m][0] * scale, o1 = r1 * ALPHA + acc[ai][bj][m][1] * scale;
;                 u32x4 w; w.x = pkh(o0[0], o0[1]); w.y = pkh(o0[2], o0[3]); w.z = pkh(o1[0], o1[1]); w.w = pkh(o1[2], o1[3]);
;                 *(u32x4*)(op + rb + bj * 128) = w; }
.LBB0_648:
	v_pk_mul_f32 v[90:91], v[90:91], s[62:63] op_sel_hi:[1,0]
	v_pk_mul_f32 v[88:89], v[88:89], s[62:63] op_sel_hi:[1,0]
	v_pk_fma_f32 v[74:75], v[74:75], s[28:29], v[90:91]
	v_pk_fma_f32 v[72:73], v[72:73], s[16:17], v[88:89]
	v_pk_mul_f32 v[88:89], v[94:95], s[62:63] op_sel_hi:[1,0]
	v_pk_mul_f32 v[90:91], v[92:93], s[62:63] op_sel_hi:[1,0]
	v_pk_fma_f32 v[88:89], v[66:67], s[28:29], v[88:89]
	v_pk_fma_f32 v[66:67], v[64:65], s[16:17], v[90:91]
	v_cvt_pk_f16_f32 v64, v72, v73
	v_cvt_pk_f16_f32 v66, v66, v67
	v_cvt_pk_f16_f32 v67, v88, v89
	v_or_b32_e32 v88, 32, v136
	v_ashrrev_i32_e32 v89, 31, v88
	v_cvt_pk_f16_f32 v65, v74, v75
	v_lshlrev_b64 v[108:109], 12, v[88:89]
	global_store_dwordx4 v[118:119], v[64:67], off offset:256
	v_mov_b32_e32 v187, v125
	v_mov_b32_e32 v104, v185
	v_lshl_add_u64 v[64:65], v[218:219], 0, v[108:109]
	s_and_b64 vcc, exec, s[8:9]
	v_mov_b64_e32 v[106:107], v[186:187]
	s_cbranch_vccnz .LBB0_650
	v_lshl_add_u64 v[88:89], v[88:89], 3, s[14:15]
	global_load_dwordx2 v[104:105], v[88:89], off
	s_waitcnt vmcnt(0)
	v_mov_b32_e32 v124, v105
	v_mov_b64_e32 v[106:107], v[124:125]
.LBB0_650:
	global_load_dwordx4 v[72:75], v[64:65], off
	s_nop 0
	global_load_dwordx4 v[64:67], v[64:65], off offset:256
	s_waitcnt vmcnt(4)
	s_mov_b64 s[0:1], -1
	s_and_b64 vcc, exec, s[12:13]
	s_cbranch_vccnz .LBB0_695
	s_andn2_b64 vcc, exec, s[0:1]
	s_cbranch_vccz .LBB0_696

; __device__ __forceinline__ float bflo(unsigned w) { return __uint_as_float(w << 16); }
; __device__ __forceinline__ float bfhi(unsigned w) { return __uint_as_float(w & 0xffff0000u); }
; __device__ __forceinline__ float hlo(unsigned w) { return (float)__builtin_bit_cast(h16x2, w)[0]; }
; __device__ __forceinline__ float hhi(unsigned w) { return (float)__builtin_bit_cast(h16x2, w)[1]; }
;     __device__ __forceinline__ void operator()(const Acc& acc, const Unit& u, int wr, int wc, int fr, int fq) const {
;     ...
;             if (gidx + 1 < 8) { const int ai2 = (gidx + 1) >> 2, m2 = (gidx + 1) & 3; const size_t row2 = (size_t)(row0 + ai2 * 128 + m2 * 16);
; #pragma unroll
;                 for (int bj = 0; bj < 2; ++bj) xv[(gidx + 1) & 1][bj] = *(const u32x4*)(xr + row2 * DM + col0 + bj * 128);
;                 mu[(gidx + 1) & 1] = 0.f; rs[(gidx + 1) & 1] = 1.f;
;                 if (stats) { mu[(gidx + 1) & 1] = stats[row2 * 2]; rs[(gidx + 1) & 1] = stats[row2 * 2 + 1]; } }
;             const size_t rb = (size_t)(row0 + ai * 128 + m * 16) * DM + col0;
; #pragma unroll
;             for (int bj = 0; bj < 2; ++bj) { const u32x4 x4 = xv[gidx & 1][bj];
;                 f32x4 r0, r1;
;                 if (x_bf16) { r0 = (f32x4){bflo(x4.x), bfhi(x4.x), bflo(x4.y), bfhi(x4.y)}; r1 = (f32x4){bflo(x4.z), bfhi(x4.z), bflo(x4.w), bfhi(x4.w)}; }
;                 else { r0 = (f32x4){hlo(x4.x), hhi(x4.x), hlo(x4.y), hhi(x4.y)}; r1 = (f32x4){hlo(x4.z), hhi(x4.z), hlo(x4.w), hhi(x4.w)}; }
;                 if (stats) { r0 = (r0 - mu[gidx & 1]) * rs[gidx & 1] * gv[bj][0] + bv[bj][0]; r1 = (r1 - mu[gidx & 1]) * rs[gidx & 1] * gv[bj][1] + bv[bj][1]; }
;                 const f32x4 o0 = r0 * ALPHA + acc[ai][bj][m][0] * scale, o1 = r1 * ALPHA + acc[ai][bj][m][1] * scale;
;                 u32x4 w; w.x = pkh(o0[0], o0[1]); w.y = pkh(o0[2], o0[3]); w.z = pkh(o1[0], o1[1]); w.w = pkh(o1[2], o1[3]);
;                 *(u32x4*)(op + rb + bj * 128) = w; }
.LBB0_658:
	v_pk_mul_f32 v[42:43], v[42:43], s[62:63] op_sel_hi:[1,0]
	v_pk_mul_f32 v[40:41], v[40:41], s[62:63] op_sel_hi:[1,0]
	v_pk_fma_f32 v[38:39], v[38:39], s[28:29], v[42:43]
	v_pk_fma_f32 v[36:37], v[36:37], s[16:17], v[40:41]
	v_pk_mul_f32 v[40:41], v[46:47], s[62:63] op_sel_hi:[1,0]
	v_pk_mul_f32 v[42:43], v[44:45], s[62:63] op_sel_hi:[1,0]
	v_pk_fma_f32 v[40:41], v[34:35], s[28:29], v[40:41]
	v_pk_fma_f32 v[34:35], v[32:33], s[16:17], v[42:43]
	v_cvt_pk_f16_f32 v32, v36, v37
	v_cvt_pk_f16_f32 v34, v34, v35
	v_cvt_pk_f16_f32 v35, v40, v41
	v_or_b32_e32 v40, 48, v136
	v_ashrrev_i32_e32 v41, 31, v40
	v_cvt_pk_f16_f32 v33, v38, v39
	v_lshlrev_b64 v[92:93], 12, v[40:41]
	global_store_dwordx4 v[102:103], v[32:35], off offset:256
	v_mov_b32_e32 v89, v185
	s_and_b64 vcc, exec, s[8:9]
	v_lshl_add_u64 v[32:33], v[218:219], 0, v[92:93]
	v_mov_b32_e32 v91, v186
	s_cbranch_vccnz .LBB0_660
	v_lshl_add_u64 v[40:41], v[40:41], 3, s[14:15]
	global_load_dwordx2 v[90:91], v[40:41], off
	s_waitcnt vmcnt(0)
	v_mov_b32_e32 v89, v90
.LBB0_660:
	global_load_dwordx4 v[36:39], v[32:33], off
	s_nop 0
	global_load_dwordx4 v[32:35], v[32:33], off offset:256
	s_waitcnt vmcnt(4)
	s_mov_b64 s[0:1], -1
	s_and_b64 vcc, exec, s[12:13]
	s_cbranch_vccnz .LBB0_699
	s_andn2_b64 vcc, exec, s[0:1]
	s_cbranch_vccz .LBB0_700
.LBB0_662:
	s_waitcnt vmcnt(4)
	v_mov_b32_e32 v72, v106
	s_and_b64 vcc, exec, s[8:9]
	v_mov_b32_e32 v73, v106
	s_cbranch_vccnz .LBB0_664

; __device__ __forceinline__ float bflo(unsigned w) { return __uint_as_float(w << 16); }
; __device__ __forceinline__ float bfhi(unsigned w) { return __uint_as_float(w & 0xffff0000u); }
; __device__ __forceinline__ float hlo(unsigned w) { return (float)__builtin_bit_cast(h16x2, w)[0]; }
; __device__ __forceinline__ float hhi(unsigned w) { return (float)__builtin_bit_cast(h16x2, w)[1]; }
;     __device__ __forceinline__ void operator()(const Acc& acc, const Unit& u, int wr, int wc, int fr, int fq) const {
;     ...
;             for (int bj = 0; bj < 2; ++bj) { const u32x4 x4 = xv[gidx & 1][bj];
;                 f32x4 r0, r1;
;                 if (x_bf16) { r0 = (f32x4){bflo(x4.x), bfhi(x4.x), bflo(x4.y), bfhi(x4.y)}; r1 = (f32x4){bflo(x4.z), bfhi(x4.z), bflo(x4.w), bfhi(x4.w)}; }
;                 else { r0 = (f32x4){hlo(x4.x), hhi(x4.x), hlo(x4.y), hhi(x4.y)}; r1 = (f32x4){hlo(x4.z), hhi(x4.z), hlo(x4.w), hhi(x4.w)}; }
;                 if (stats) { r0 = (r0 - mu[gidx & 1]) * rs[gidx & 1] * gv[bj][0] + bv[bj][0]; r1 = (r1 - mu[gidx & 1]) * rs[gidx & 1] * gv[bj][1] + bv[bj][1]; }
;                 const f32x4 o0 = r0 * ALPHA + acc[ai][bj][m][0] * scale, o1 = r1 * ALPHA + acc[ai][bj][m][1] * scale;
;                 u32x4 w; w.x = pkh(o0[0], o0[1]); w.y = pkh(o0[2], o0[3]); w.z = pkh(o1[0], o1[1]); w.w = pkh(o1[2], o1[3]);
;                 *(u32x4*)(op + rb + bj * 128) = w; }
.LBB0_668:
	v_pk_mul_f32 v[26:27], v[26:27], s[62:63] op_sel_hi:[1,0]
	v_pk_mul_f32 v[24:25], v[24:25], s[62:63] op_sel_hi:[1,0]
	v_pk_fma_f32 v[22:23], v[22:23], s[28:29], v[26:27]
	v_pk_fma_f32 v[20:21], v[20:21], s[16:17], v[24:25]
	v_pk_mul_f32 v[24:25], v[30:31], s[62:63] op_sel_hi:[1,0]
	v_pk_mul_f32 v[26:27], v[28:29], s[62:63] op_sel_hi:[1,0]
	v_pk_fma_f32 v[24:25], v[18:19], s[28:29], v[24:25]
	v_pk_fma_f32 v[18:19], v[16:17], s[16:17], v[26:27]
	v_cvt_pk_f16_f32 v16, v20, v21
	v_cvt_pk_f16_f32 v17, v22, v23
	v_cvt_pk_f16_f32 v18, v18, v19
	v_cvt_pk_f16_f32 v19, v24, v25
	s_mov_b64 s[0:1], -1
	s_and_b64 vcc, exec, s[12:13]
	global_store_dwordx4 v[74:75], v[16:19], off offset:256
	s_waitcnt vmcnt(2)
	s_cbranch_vccnz .LBB0_703
	s_andn2_b64 vcc, exec, s[0:1]
	s_cbranch_vccz .LBB0_704

; __device__ __forceinline__ float bflo(unsigned w) { return __uint_as_float(w << 16); }
; __device__ __forceinline__ float bfhi(unsigned w) { return __uint_as_float(w & 0xffff0000u); }
; __device__ __forceinline__ float hlo(unsigned w) { return (float)__builtin_bit_cast(h16x2, w)[0]; }
; __device__ __forceinline__ float hhi(unsigned w) { return (float)__builtin_bit_cast(h16x2, w)[1]; }
;     __device__ __forceinline__ void operator()(const Acc& acc, const Unit& u, int wr, int wc, int fr, int fq) const {
;     ...
;             for (int bj = 0; bj < 2; ++bj) { const u32x4 x4 = xv[gidx & 1][bj];
;                 f32x4 r0, r1;
;                 if (x_bf16) { r0 = (f32x4){bflo(x4.x), bfhi(x4.x), bflo(x4.y), bfhi(x4.y)}; r1 = (f32x4){bflo(x4.z), bfhi(x4.z), bflo(x4.w), bfhi(x4.w)}; }
;                 else { r0 = (f32x4){hlo(x4.x), hhi(x4.x), hlo(x4.y), hhi(x4.y)}; r1 = (f32x4){hlo(x4.z), hhi(x4.z), hlo(x4.w), hhi(x4.w)}; }
;                 if (stats) { r0 = (r0 - mu[gidx & 1]) * rs[gidx & 1] * gv[bj][0] + bv[bj][0]; r1 = (r1 - mu[gidx & 1]) * rs[gidx & 1] * gv[bj][1] + bv[bj][1]; }
.LBB0_683:
	s_waitcnt vmcnt(4)
	v_cvt_f32_f16_sdwa v137, v148 dst_sel:DWORD dst_unused:UNUSED_PAD src0_sel:WORD_1
	v_cvt_f32_f16_e32 v136, v148
	v_cvt_f32_f16_sdwa v139, v149 dst_sel:DWORD dst_unused:UNUSED_PAD src0_sel:WORD_1
	v_cvt_f32_f16_e32 v138, v149
	v_cvt_f32_f16_sdwa v141, v150 dst_sel:DWORD dst_unused:UNUSED_PAD src0_sel:WORD_1
	v_cvt_f32_f16_e32 v140, v150
	v_cvt_f32_f16_sdwa v143, v151 dst_sel:DWORD dst_unused:UNUSED_PAD src0_sel:WORD_1
	v_cvt_f32_f16_e32 v142, v151
	s_cbranch_execnz .LBB0_622
.LBB0_684:
	s_waitcnt vmcnt(4)
	v_lshlrev_b32_e32 v136, 16, v148
	v_and_b32_e32 v137, 0xffff0000, v148
	v_lshlrev_b32_e32 v138, 16, v149
	v_and_b32_e32 v139, 0xffff0000, v149
	v_lshlrev_b32_e32 v140, 16, v150
	v_and_b32_e32 v141, 0xffff0000, v150
	v_lshlrev_b32_e32 v142, 16, v151
	v_and_b32_e32 v143, 0xffff0000, v151
	v_mov_b32_e32 v148, v170
	s_and_b64 vcc, exec, s[8:9]
	v_mov_b32_e32 v149, v170
	s_cbranch_vccz .LBB0_623
	s_branch .LBB0_624

; __device__ __forceinline__ float bflo(unsigned w) { return __uint_as_float(w << 16); }
; __device__ __forceinline__ float bfhi(unsigned w) { return __uint_as_float(w & 0xffff0000u); }
; __device__ __forceinline__ float hlo(unsigned w) { return (float)__builtin_bit_cast(h16x2, w)[0]; }
; __device__ __forceinline__ float hhi(unsigned w) { return (float)__builtin_bit_cast(h16x2, w)[1]; }
;     __device__ __forceinline__ void operator()(const Acc& acc, const Unit& u, int wr, int wc, int fr, int fq) const {
;     ...
;             for (int bj = 0; bj < 2; ++bj) { const u32x4 x4 = xv[gidx & 1][bj];
;                 f32x4 r0, r1;
;                 if (x_bf16) { r0 = (f32x4){bflo(x4.x), bfhi(x4.x), bflo(x4.y), bfhi(x4.y)}; r1 = (f32x4){bflo(x4.z), bfhi(x4.z), bflo(x4.w), bfhi(x4.w)}; }
;                 else { r0 = (f32x4){hlo(x4.x), hhi(x4.x), hlo(x4.y), hhi(x4.y)}; r1 = (f32x4){hlo(x4.z), hhi(x4.z), hlo(x4.w), hhi(x4.w)}; }
;                 if (stats) { r0 = (r0 - mu[gidx & 1]) * rs[gidx & 1] * gv[bj][0] + bv[bj][0]; r1 = (r1 - mu[gidx & 1]) * rs[gidx & 1] * gv[bj][1] + bv[bj][1]; }
.LBB0_691:
	s_waitcnt vmcnt(4)
	v_cvt_f32_f16_sdwa v105, v116 dst_sel:DWORD dst_unused:UNUSED_PAD src0_sel:WORD_1
	v_cvt_f32_f16_e32 v104, v116
	v_cvt_f32_f16_sdwa v107, v117 dst_sel:DWORD dst_unused:UNUSED_PAD src0_sel:WORD_1
	v_cvt_f32_f16_e32 v106, v117
	v_cvt_f32_f16_sdwa v109, v118 dst_sel:DWORD dst_unused:UNUSED_PAD src0_sel:WORD_1
	v_cvt_f32_f16_e32 v108, v118
	v_cvt_f32_f16_sdwa v111, v119 dst_sel:DWORD dst_unused:UNUSED_PAD src0_sel:WORD_1
	v_cvt_f32_f16_e32 v110, v119
	s_cbranch_execnz .LBB0_642
.LBB0_692:
	s_waitcnt vmcnt(4)
	v_lshlrev_b32_e32 v104, 16, v116
	v_and_b32_e32 v105, 0xffff0000, v116
	v_lshlrev_b32_e32 v106, 16, v117
	v_and_b32_e32 v107, 0xffff0000, v117
	v_lshlrev_b32_e32 v108, 16, v118
	v_and_b32_e32 v109, 0xffff0000, v118
	v_lshlrev_b32_e32 v110, 16, v119
	v_and_b32_e32 v111, 0xffff0000, v119
	v_mov_b32_e32 v116, v140
	s_and_b64 vcc, exec, s[8:9]
	v_mov_b32_e32 v117, v140
	s_cbranch_vccz .LBB0_643
	s_branch .LBB0_644

; __device__ __forceinline__ float bflo(unsigned w) { return __uint_as_float(w << 16); }
; __device__ __forceinline__ float bfhi(unsigned w) { return __uint_as_float(w & 0xffff0000u); }
; __device__ __forceinline__ float hlo(unsigned w) { return (float)__builtin_bit_cast(h16x2, w)[0]; }
; __device__ __forceinline__ float hhi(unsigned w) { return (float)__builtin_bit_cast(h16x2, w)[1]; }
;     __device__ __forceinline__ void operator()(const Acc& acc, const Unit& u, int wr, int wc, int fr, int fq) const {
;     ...
;             for (int bj = 0; bj < 2; ++bj) { const u32x4 x4 = xv[gidx & 1][bj];
;                 f32x4 r0, r1;
;                 if (x_bf16) { r0 = (f32x4){bflo(x4.x), bfhi(x4.x), bflo(x4.y), bfhi(x4.y)}; r1 = (f32x4){bflo(x4.z), bfhi(x4.z), bflo(x4.w), bfhi(x4.w)}; }
;                 else { r0 = (f32x4){hlo(x4.x), hhi(x4.x), hlo(x4.y), hhi(x4.y)}; r1 = (f32x4){hlo(x4.z), hhi(x4.z), hlo(x4.w), hhi(x4.w)}; }
;                 if (stats) { r0 = (r0 - mu[gidx & 1]) * rs[gidx & 1] * gv[bj][0] + bv[bj][0]; r1 = (r1 - mu[gidx & 1]) * rs[gidx & 1] * gv[bj][1] + bv[bj][1]; }
.LBB0_699:
	s_waitcnt vmcnt(4)
	v_cvt_f32_f16_sdwa v41, v72 dst_sel:DWORD dst_unused:UNUSED_PAD src0_sel:WORD_1
	v_cvt_f32_f16_e32 v40, v72
	v_cvt_f32_f16_sdwa v43, v73 dst_sel:DWORD dst_unused:UNUSED_PAD src0_sel:WORD_1
	v_cvt_f32_f16_e32 v42, v73
	v_cvt_f32_f16_sdwa v45, v74 dst_sel:DWORD dst_unused:UNUSED_PAD src0_sel:WORD_1
	v_cvt_f32_f16_e32 v44, v74
	v_cvt_f32_f16_sdwa v47, v75 dst_sel:DWORD dst_unused:UNUSED_PAD src0_sel:WORD_1
	v_cvt_f32_f16_e32 v46, v75
	s_cbranch_execnz .LBB0_662
.LBB0_700:
	s_waitcnt vmcnt(4)
	v_lshlrev_b32_e32 v40, 16, v72
	v_and_b32_e32 v41, 0xffff0000, v72
	v_lshlrev_b32_e32 v42, 16, v73
	v_and_b32_e32 v43, 0xffff0000, v73
	v_lshlrev_b32_e32 v44, 16, v74
	v_and_b32_e32 v45, 0xffff0000, v74
	v_lshlrev_b32_e32 v46, 16, v75
	v_and_b32_e32 v47, 0xffff0000, v75
	v_mov_b32_e32 v72, v106
	s_and_b64 vcc, exec, s[8:9]
	v_mov_b32_e32 v73, v106
	s_cbranch_vccz .LBB0_663
	s_branch .LBB0_664
